# loop-invariant LDS fragment address adds hoisted out of the P4 (all 16) and P3 (4) K-loops as well
# baseline (speedup 1.0000x reference)
.LBB0_778:
	s_lshl_b32 s35, s91, 18
	s_lshl_b32 s92, s34, 8
	s_add_i32 s35, s35, s92
	v_mov_b32_e32 v6, v5
	v_mov_b32_e32 v7, v5
	s_add_u32 s93, s26, 0x100
	v_mov_b32_e32 v4, v5
	v_mov_b64_e32 v[10:11], v[6:7]
	v_mov_b64_e32 v[14:15], v[6:7]
	v_mov_b64_e32 v[26:27], v[6:7]
	v_mov_b64_e32 v[30:31], v[6:7]
	v_mov_b64_e32 v[42:43], v[6:7]
	v_mov_b64_e32 v[46:47], v[6:7]
	v_mov_b64_e32 v[58:59], v[6:7]
	v_mov_b64_e32 v[62:63], v[6:7]
	v_mov_b64_e32 v[18:19], v[6:7]
	v_mov_b64_e32 v[22:23], v[6:7]
	v_mov_b64_e32 v[34:35], v[6:7]
	v_mov_b64_e32 v[38:39], v[6:7]
	v_mov_b64_e32 v[50:51], v[6:7]
	v_mov_b64_e32 v[54:55], v[6:7]
	v_mov_b64_e32 v[66:67], v[6:7]
	v_mov_b64_e32 v[70:71], v[6:7]
	v_mov_b64_e32 v[74:75], v[6:7]
	v_mov_b64_e32 v[78:79], v[6:7]
	v_mov_b64_e32 v[90:91], v[6:7]
	v_mov_b64_e32 v[94:95], v[6:7]
	v_mov_b64_e32 v[106:107], v[6:7]
	v_mov_b64_e32 v[110:111], v[6:7]
	v_mov_b64_e32 v[122:123], v[6:7]
	v_mov_b64_e32 v[126:127], v[6:7]
	v_mov_b64_e32 v[82:83], v[6:7]
	v_mov_b64_e32 v[86:87], v[6:7]
	v_mov_b64_e32 v[98:99], v[6:7]
	v_mov_b64_e32 v[102:103], v[6:7]
	v_mov_b64_e32 v[114:115], v[6:7]
	v_mov_b64_e32 v[118:119], v[6:7]
	v_mov_b64_e32 v[130:131], v[6:7]
	v_mov_b64_e32 v[134:135], v[6:7]
	v_add_u32_e32 v178, s35, v175
	v_lshl_add_u64 v[170:171], s[28:29], 0, v[152:153]
	s_addc_u32 s94, s27, 0
	s_mov_b32 s95, -2
	s_mov_b64 s[64:65], 0
	v_mov_b64_e32 v[8:9], v[4:5]
	v_mov_b64_e32 v[12:13], v[4:5]
	v_mov_b64_e32 v[24:25], v[4:5]
	v_mov_b64_e32 v[28:29], v[4:5]
	v_mov_b64_e32 v[40:41], v[4:5]
	v_mov_b64_e32 v[44:45], v[4:5]
	v_mov_b64_e32 v[56:57], v[4:5]
	v_mov_b64_e32 v[60:61], v[4:5]
	v_mov_b64_e32 v[16:17], v[4:5]
	v_mov_b64_e32 v[20:21], v[4:5]
	v_mov_b64_e32 v[32:33], v[4:5]
	v_mov_b64_e32 v[36:37], v[4:5]
	v_mov_b64_e32 v[48:49], v[4:5]
	v_mov_b64_e32 v[52:53], v[4:5]
	v_mov_b64_e32 v[64:65], v[4:5]
	v_mov_b64_e32 v[68:69], v[4:5]
	v_mov_b64_e32 v[72:73], v[4:5]
	v_mov_b64_e32 v[76:77], v[4:5]
	v_mov_b64_e32 v[88:89], v[4:5]
	v_mov_b64_e32 v[92:93], v[4:5]
	v_mov_b64_e32 v[104:105], v[4:5]
	v_mov_b64_e32 v[108:109], v[4:5]
	v_mov_b64_e32 v[120:121], v[4:5]
	v_mov_b64_e32 v[124:125], v[4:5]
	v_mov_b64_e32 v[80:81], v[4:5]
	v_mov_b64_e32 v[84:85], v[4:5]
	v_mov_b64_e32 v[96:97], v[4:5]
	v_mov_b64_e32 v[100:101], v[4:5]
	v_mov_b64_e32 v[112:113], v[4:5]
	v_mov_b64_e32 v[116:117], v[4:5]
	v_mov_b64_e32 v[128:129], v[4:5]
	v_mov_b64_e32 v[132:133], v[4:5]
	v_add_u32_e32 v250, s73, v159
	v_add_u32_e32 v251, s73, v173
	v_add_u32_e32 v252, s77, v159
	v_add_u32_e32 v253, s77, v173
	s_branch .LBB0_780
.LBB0_779:
	ds_read_b128 v[136:139], v250
	ds_read_b128 v[140:143], v251
	s_add_u32 s26, s28, s64
	ds_read_b128 v[180:183], v252
	ds_read_b128 v[196:199], v253
	v_add_u32_e32 v4, s79, v159
	s_addc_u32 s27, s29, s65
	v_add_u32_e32 v6, s79, v173
	ds_read_b128 v[200:203], v4
	ds_read_b128 v[204:207], v6
	v_add_u32_e32 v4, s80, v159
	s_add_u32 s26, s26, 0x100
	v_add_u32_e32 v6, s80, v173
	ds_read_b128 v[208:211], v4
	ds_read_b128 v[212:215], v6
	s_addc_u32 s27, s27, 0
	s_add_u32 s34, s93, s64
	s_addc_u32 s35, s94, s65
	s_cmpk_eq_i32 s64, 0xb00
	s_cselect_b32 s35, s63, s35
	s_cselect_b32 s34, s62, s34
	s_cselect_b32 s27, s1, s27
	s_cselect_b32 s26, s0, s26
	v_lshl_add_u64 v[6:7], v[170:171], 0, s[64:65]
	v_lshl_add_u64 v[184:185], v[6:7], 0, s[24:25]
	s_add_i32 m0, s66, 0x8000
	s_mov_b64 s[38:39], 0x30080
	ds_read_b128 v[216:219], v176
	ds_read_b128 v[220:223], v176 offset:2048
	ds_read_b128 v[224:227], v177
	ds_read_b128 v[228:231], v177 offset:2048
	ds_read_b128 v[232:235], v176 offset:4096
	ds_read_b128 v[236:239], v176 offset:6144
	ds_read_b128 v[240:243], v177 offset:4096
	ds_read_b128 v[244:247], v177 offset:6144
	global_load_lds_dwordx4 v[184:185], off
	v_lshl_add_u64 v[184:185], v[6:7], 0, s[38:39]
	s_add_i32 m0, s66, 0xa000
	s_mov_b64 s[38:39], 0x90080
	global_load_lds_dwordx4 v[184:185], off
	v_lshl_add_u64 v[184:185], v[6:7], 0, s[50:51]
	s_add_i32 m0, s66, 0xc000
	v_lshl_add_u64 v[6:7], v[6:7], 0, s[38:39]
	global_load_lds_dwordx4 v[184:185], off
	s_add_i32 m0, s66, 0xe000
	s_nop 0
	global_load_lds_dwordx4 v[6:7], off
	s_waitcnt vmcnt(8)
	s_waitcnt lgkmcnt(0)
	s_barrier
	v_mfma_f32_16x16x32_bf16 v[132:135], v[136:139], v[216:219], v[132:135]
	v_mfma_f32_16x16x32_bf16 v[132:135], v[140:143], v[224:227], v[132:135]
	v_mfma_f32_16x16x32_bf16 v[116:119], v[140:143], v[228:231], v[116:119]
	v_mfma_f32_16x16x32_bf16 v[116:119], v[136:139], v[220:223], v[116:119]
	v_mfma_f32_16x16x32_bf16 v[100:103], v[136:139], v[232:235], v[100:103]
	v_mfma_f32_16x16x32_bf16 v[100:103], v[140:143], v[240:243], v[100:103]
	v_mfma_f32_16x16x32_bf16 v[84:87], v[140:143], v[244:247], v[84:87]
	v_mfma_f32_16x16x32_bf16 v[84:87], v[136:139], v[236:239], v[84:87]
	v_mfma_f32_16x16x32_bf16 v[80:83], v[180:183], v[236:239], v[80:83]
	v_mfma_f32_16x16x32_bf16 v[80:83], v[196:199], v[244:247], v[80:83]
	v_mfma_f32_16x16x32_bf16 v[96:99], v[196:199], v[240:243], v[96:99]
	v_mfma_f32_16x16x32_bf16 v[96:99], v[180:183], v[232:235], v[96:99]
	v_mfma_f32_16x16x32_bf16 v[112:115], v[180:183], v[220:223], v[112:115]
	v_mfma_f32_16x16x32_bf16 v[112:115], v[196:199], v[228:231], v[112:115]
	v_mfma_f32_16x16x32_bf16 v[128:131], v[196:199], v[224:227], v[128:131]
	v_mfma_f32_16x16x32_bf16 v[128:131], v[180:183], v[216:219], v[128:131]
	v_mfma_f32_16x16x32_bf16 v[124:127], v[200:203], v[216:219], v[124:127]
	v_mfma_f32_16x16x32_bf16 v[124:127], v[204:207], v[224:227], v[124:127]
	v_mfma_f32_16x16x32_bf16 v[108:111], v[204:207], v[228:231], v[108:111]
	v_mfma_f32_16x16x32_bf16 v[108:111], v[200:203], v[220:223], v[108:111]
	v_mfma_f32_16x16x32_bf16 v[92:95], v[200:203], v[232:235], v[92:95]
	v_mfma_f32_16x16x32_bf16 v[92:95], v[204:207], v[240:243], v[92:95]
	v_mfma_f32_16x16x32_bf16 v[76:79], v[204:207], v[244:247], v[76:79]
	v_mfma_f32_16x16x32_bf16 v[76:79], v[200:203], v[236:239], v[76:79]
	v_mfma_f32_16x16x32_bf16 v[72:75], v[208:211], v[236:239], v[72:75]
	v_mfma_f32_16x16x32_bf16 v[72:75], v[212:215], v[244:247], v[72:75]
	v_mfma_f32_16x16x32_bf16 v[88:91], v[212:215], v[240:243], v[88:91]
	v_mfma_f32_16x16x32_bf16 v[88:91], v[208:211], v[232:235], v[88:91]
	v_mfma_f32_16x16x32_bf16 v[104:107], v[208:211], v[220:223], v[104:107]
	v_mfma_f32_16x16x32_bf16 v[104:107], v[212:215], v[228:231], v[104:107]
	v_mfma_f32_16x16x32_bf16 v[120:123], v[212:215], v[224:227], v[120:123]
	v_mfma_f32_16x16x32_bf16 v[120:123], v[208:211], v[216:219], v[120:123]
	s_barrier
	v_lshl_add_u64 v[184:185], s[34:35], 0, v[146:147]
	s_add_i32 s34, s73, s3
	s_mov_b32 m0, s34
	ds_read_b128 v[216:219], v176 offset:16384
	ds_read_b128 v[220:223], v176 offset:18432
	ds_read_b128 v[224:227], v177 offset:16384
	ds_read_b128 v[228:231], v177 offset:18432
	ds_read_b128 v[232:235], v176 offset:20480
	ds_read_b128 v[236:239], v176 offset:22528
	ds_read_b128 v[240:243], v177 offset:20480
	ds_read_b128 v[244:247], v177 offset:22528
	global_load_lds_dwordx4 v[184:185], off
	v_lshl_add_u64 v[6:7], v[184:185], 0, s[12:13]
	s_add_i32 m0, s34, 0x2000
	s_add_i32 s34, s79, s3
	global_load_lds_dwordx4 v[6:7], off
	v_lshl_add_u64 v[6:7], v[184:185], 0, s[14:15]
	s_mov_b32 m0, s34
	s_nop 0
	global_load_lds_dwordx4 v[6:7], off
	v_lshl_add_u64 v[6:7], v[184:185], 0, s[16:17]
	s_add_i32 m0, s34, 0x2000
	s_nop 0
	global_load_lds_dwordx4 v[6:7], off
	s_waitcnt vmcnt(4)
	s_waitcnt lgkmcnt(0)
	s_barrier
	v_mfma_f32_16x16x32_bf16 v[68:71], v[136:139], v[216:219], v[68:71]
	v_mfma_f32_16x16x32_bf16 v[68:71], v[140:143], v[224:227], v[68:71]
	v_mfma_f32_16x16x32_bf16 v[52:55], v[140:143], v[228:231], v[52:55]
	v_mfma_f32_16x16x32_bf16 v[52:55], v[136:139], v[220:223], v[52:55]
	v_mfma_f32_16x16x32_bf16 v[36:39], v[136:139], v[232:235], v[36:39]
	v_mfma_f32_16x16x32_bf16 v[36:39], v[140:143], v[240:243], v[36:39]
	v_mfma_f32_16x16x32_bf16 v[20:23], v[140:143], v[244:247], v[20:23]
	v_mfma_f32_16x16x32_bf16 v[20:23], v[136:139], v[236:239], v[20:23]
	v_mfma_f32_16x16x32_bf16 v[16:19], v[180:183], v[236:239], v[16:19]
	v_mfma_f32_16x16x32_bf16 v[16:19], v[196:199], v[244:247], v[16:19]
	v_mfma_f32_16x16x32_bf16 v[32:35], v[196:199], v[240:243], v[32:35]
	v_mfma_f32_16x16x32_bf16 v[32:35], v[180:183], v[232:235], v[32:35]
	v_mfma_f32_16x16x32_bf16 v[48:51], v[180:183], v[220:223], v[48:51]
	v_mfma_f32_16x16x32_bf16 v[48:51], v[196:199], v[228:231], v[48:51]
	v_mfma_f32_16x16x32_bf16 v[64:67], v[196:199], v[224:227], v[64:67]
	v_mfma_f32_16x16x32_bf16 v[64:67], v[180:183], v[216:219], v[64:67]
	v_mfma_f32_16x16x32_bf16 v[60:63], v[200:203], v[216:219], v[60:63]
	v_mfma_f32_16x16x32_bf16 v[60:63], v[204:207], v[224:227], v[60:63]
	v_mfma_f32_16x16x32_bf16 v[56:59], v[208:211], v[216:219], v[56:59]
	v_mfma_f32_16x16x32_bf16 v[56:59], v[212:215], v[224:227], v[56:59]
	v_mfma_f32_16x16x32_bf16 v[44:47], v[200:203], v[220:223], v[44:47]
	v_mfma_f32_16x16x32_bf16 v[44:47], v[204:207], v[228:231], v[44:47]
	v_mfma_f32_16x16x32_bf16 v[40:43], v[208:211], v[220:223], v[40:43]
	v_mfma_f32_16x16x32_bf16 v[40:43], v[212:215], v[228:231], v[40:43]
	v_mfma_f32_16x16x32_bf16 v[28:31], v[200:203], v[232:235], v[28:31]
	v_mfma_f32_16x16x32_bf16 v[28:31], v[204:207], v[240:243], v[28:31]
	v_mfma_f32_16x16x32_bf16 v[24:27], v[208:211], v[232:235], v[24:27]
	v_mfma_f32_16x16x32_bf16 v[24:27], v[212:215], v[240:243], v[24:27]
	v_mfma_f32_16x16x32_bf16 v[12:15], v[200:203], v[236:239], v[12:15]
	v_mfma_f32_16x16x32_bf16 v[12:15], v[204:207], v[244:247], v[12:15]
	v_mfma_f32_16x16x32_bf16 v[6:9], v[208:211], v[236:239], v[8:11]
	v_mfma_f32_16x16x32_bf16 v[6:9], v[212:215], v[244:247], v[6:9]
	s_barrier
	v_add_u32_e32 v4, s83, v159
	v_add_u32_e32 v10, s83, v173
	ds_read_b128 v[136:139], v4
	ds_read_b128 v[140:143], v10
	v_add_u32_e32 v4, s81, v159
	v_add_u32_e32 v10, s81, v173
	ds_read_b128 v[180:183], v4
	ds_read_b128 v[196:199], v10
	v_add_u32_e32 v4, s84, v159
	v_add_u32_e32 v10, s84, v173
	ds_read_b128 v[200:203], v4
	ds_read_b128 v[204:207], v10
	v_add_u32_e32 v4, s82, v159
	v_add_u32_e32 v10, s82, v173
	ds_read_b128 v[208:211], v4
	ds_read_b128 v[212:215], v10
	s_mov_b32 m0, s66
	v_lshl_add_u64 v[10:11], s[26:27], 0, v[144:145]
	ds_read_b128 v[216:219], v176 offset:32768
	ds_read_b128 v[220:223], v176 offset:34816
	ds_read_b128 v[224:227], v177 offset:32768
	ds_read_b128 v[228:231], v177 offset:34816
	ds_read_b128 v[232:235], v176 offset:36864
	ds_read_b128 v[236:239], v176 offset:38912
	ds_read_b128 v[240:243], v177 offset:36864
	ds_read_b128 v[244:247], v177 offset:38912
	global_load_lds_dwordx4 v[10:11], off
	v_lshl_add_u64 v[248:249], v[10:11], 0, s[18:19]
	s_mov_b32 m0, s67
	s_nop 0
	global_load_lds_dwordx4 v[248:249], off
	v_lshl_add_u64 v[248:249], v[10:11], 0, s[12:13]
	s_mov_b32 m0, s68
	v_lshl_add_u64 v[10:11], v[10:11], 0, s[20:21]
	global_load_lds_dwordx4 v[248:249], off
	s_mov_b32 m0, s69
	s_nop 0
	global_load_lds_dwordx4 v[10:11], off
	s_waitcnt vmcnt(8)
	s_waitcnt lgkmcnt(0)
	s_barrier
	v_mfma_f32_16x16x32_bf16 v[132:135], v[136:139], v[216:219], v[132:135]
	v_mfma_f32_16x16x32_bf16 v[132:135], v[140:143], v[224:227], v[132:135]
	v_mfma_f32_16x16x32_bf16 v[116:119], v[140:143], v[228:231], v[116:119]
	v_mfma_f32_16x16x32_bf16 v[116:119], v[136:139], v[220:223], v[116:119]
	v_mfma_f32_16x16x32_bf16 v[100:103], v[136:139], v[232:235], v[100:103]
	v_mfma_f32_16x16x32_bf16 v[100:103], v[140:143], v[240:243], v[100:103]
	v_mfma_f32_16x16x32_bf16 v[84:87], v[140:143], v[244:247], v[84:87]
	v_mfma_f32_16x16x32_bf16 v[84:87], v[136:139], v[236:239], v[84:87]
	v_mfma_f32_16x16x32_bf16 v[80:83], v[180:183], v[236:239], v[80:83]
	v_mfma_f32_16x16x32_bf16 v[80:83], v[196:199], v[244:247], v[80:83]
	v_mfma_f32_16x16x32_bf16 v[96:99], v[196:199], v[240:243], v[96:99]
	v_mfma_f32_16x16x32_bf16 v[96:99], v[180:183], v[232:235], v[96:99]
	v_mfma_f32_16x16x32_bf16 v[112:115], v[180:183], v[220:223], v[112:115]
	v_mfma_f32_16x16x32_bf16 v[112:115], v[196:199], v[228:231], v[112:115]
	v_mfma_f32_16x16x32_bf16 v[128:131], v[196:199], v[224:227], v[128:131]
	v_mfma_f32_16x16x32_bf16 v[128:131], v[180:183], v[216:219], v[128:131]
	v_mfma_f32_16x16x32_bf16 v[124:127], v[200:203], v[216:219], v[124:127]
	v_mfma_f32_16x16x32_bf16 v[124:127], v[204:207], v[224:227], v[124:127]
	v_mfma_f32_16x16x32_bf16 v[108:111], v[204:207], v[228:231], v[108:111]
	v_mfma_f32_16x16x32_bf16 v[108:111], v[200:203], v[220:223], v[108:111]
	v_mfma_f32_16x16x32_bf16 v[92:95], v[200:203], v[232:235], v[92:95]
	v_mfma_f32_16x16x32_bf16 v[92:95], v[204:207], v[240:243], v[92:95]
	v_mfma_f32_16x16x32_bf16 v[76:79], v[204:207], v[244:247], v[76:79]
	v_mfma_f32_16x16x32_bf16 v[76:79], v[200:203], v[236:239], v[76:79]
	v_mfma_f32_16x16x32_bf16 v[72:75], v[208:211], v[236:239], v[72:75]
	v_mfma_f32_16x16x32_bf16 v[72:75], v[212:215], v[244:247], v[72:75]
	v_mfma_f32_16x16x32_bf16 v[88:91], v[212:215], v[240:243], v[88:91]
	v_mfma_f32_16x16x32_bf16 v[88:91], v[208:211], v[232:235], v[88:91]
	v_mfma_f32_16x16x32_bf16 v[104:107], v[208:211], v[220:223], v[104:107]
	v_mfma_f32_16x16x32_bf16 v[104:107], v[212:215], v[228:231], v[104:107]
	v_mfma_f32_16x16x32_bf16 v[120:123], v[212:215], v[224:227], v[120:123]
	v_mfma_f32_16x16x32_bf16 v[120:123], v[208:211], v[216:219], v[120:123]
	s_barrier
	s_add_i32 s26, s83, s3
	v_lshl_add_u64 v[10:11], v[184:185], 0, s[24:25]
	s_mov_b32 m0, s26
	ds_read_b128 v[216:219], v176 offset:49152
	ds_read_b128 v[220:223], v176 offset:51200
	ds_read_b128 v[224:227], v177 offset:49152
	ds_read_b128 v[228:231], v177 offset:51200
	ds_read_b128 v[232:235], v176 offset:53248
	ds_read_b128 v[236:239], v176 offset:55296
	ds_read_b128 v[240:243], v177 offset:53248
	ds_read_b128 v[244:247], v177 offset:55296
	global_load_lds_dwordx4 v[10:11], off
	v_lshl_add_u64 v[10:11], v[184:185], 0, s[50:51]
	s_add_i32 m0, s26, 0x2000
	s_add_i32 s26, s84, s3
	global_load_lds_dwordx4 v[10:11], off
	v_lshl_add_u64 v[10:11], v[184:185], 0, s[52:53]
	s_mov_b32 m0, s26
	s_nop 0
	global_load_lds_dwordx4 v[10:11], off
	v_lshl_add_u64 v[10:11], v[184:185], 0, s[54:55]
	s_add_i32 m0, s26, 0x2000
	s_nop 0
	global_load_lds_dwordx4 v[10:11], off
	s_waitcnt vmcnt(4)
	s_waitcnt lgkmcnt(0)
	s_barrier
	v_mfma_f32_16x16x32_bf16 v[68:71], v[136:139], v[216:219], v[68:71]
	v_mfma_f32_16x16x32_bf16 v[68:71], v[140:143], v[224:227], v[68:71]
	v_mfma_f32_16x16x32_bf16 v[52:55], v[140:143], v[228:231], v[52:55]
	v_mfma_f32_16x16x32_bf16 v[52:55], v[136:139], v[220:223], v[52:55]
	v_mfma_f32_16x16x32_bf16 v[36:39], v[136:139], v[232:235], v[36:39]
	v_mfma_f32_16x16x32_bf16 v[36:39], v[140:143], v[240:243], v[36:39]
	v_mfma_f32_16x16x32_bf16 v[20:23], v[140:143], v[244:247], v[20:23]
	v_mfma_f32_16x16x32_bf16 v[20:23], v[136:139], v[236:239], v[20:23]
	v_mfma_f32_16x16x32_bf16 v[16:19], v[180:183], v[236:239], v[16:19]
	v_mfma_f32_16x16x32_bf16 v[16:19], v[196:199], v[244:247], v[16:19]
	v_mfma_f32_16x16x32_bf16 v[32:35], v[196:199], v[240:243], v[32:35]
	v_mfma_f32_16x16x32_bf16 v[32:35], v[180:183], v[232:235], v[32:35]
	v_mfma_f32_16x16x32_bf16 v[48:51], v[180:183], v[220:223], v[48:51]
	v_mfma_f32_16x16x32_bf16 v[48:51], v[196:199], v[228:231], v[48:51]
	v_mfma_f32_16x16x32_bf16 v[64:67], v[196:199], v[224:227], v[64:67]
	v_mfma_f32_16x16x32_bf16 v[64:67], v[180:183], v[216:219], v[64:67]
	v_mfma_f32_16x16x32_bf16 v[60:63], v[200:203], v[216:219], v[60:63]
	v_mfma_f32_16x16x32_bf16 v[60:63], v[204:207], v[224:227], v[60:63]
	v_mfma_f32_16x16x32_bf16 v[56:59], v[208:211], v[216:219], v[56:59]
	v_mfma_f32_16x16x32_bf16 v[56:59], v[212:215], v[224:227], v[56:59]
	v_mfma_f32_16x16x32_bf16 v[44:47], v[200:203], v[220:223], v[44:47]
	v_mfma_f32_16x16x32_bf16 v[44:47], v[204:207], v[228:231], v[44:47]
	v_mfma_f32_16x16x32_bf16 v[40:43], v[208:211], v[220:223], v[40:43]
	v_mfma_f32_16x16x32_bf16 v[40:43], v[212:215], v[228:231], v[40:43]
	v_mfma_f32_16x16x32_bf16 v[28:31], v[200:203], v[232:235], v[28:31]
	v_mfma_f32_16x16x32_bf16 v[28:31], v[204:207], v[240:243], v[28:31]
	v_mfma_f32_16x16x32_bf16 v[24:27], v[208:211], v[232:235], v[24:27]
	v_mfma_f32_16x16x32_bf16 v[24:27], v[212:215], v[240:243], v[24:27]
	v_mfma_f32_16x16x32_bf16 v[10:13], v[200:203], v[236:239], v[12:15]
	v_mfma_f32_16x16x32_bf16 v[12:15], v[204:207], v[244:247], v[10:13]
	v_mfma_f32_16x16x32_bf16 v[6:9], v[208:211], v[236:239], v[6:9]
	v_mfma_f32_16x16x32_bf16 v[8:11], v[212:215], v[244:247], v[6:9]
	s_barrier
	s_add_i32 s95, s95, 2
	s_add_u32 s64, s64, 0x100
	s_addc_u32 s65, s65, 0
	s_cmp_gt_u32 s95, 21
	s_cbranch_scc1 .LBB0_782

.LBB0_972:
	s_add_u32 s65, s26, 0x100
	s_addc_u32 s85, s27, 0
	s_ashr_i32 s63, s62, 31
	s_lshl_b64 s[66:67], s[62:63], 19
	s_add_u32 s68, s40, s66
	s_addc_u32 s69, s41, s67
	s_and_b64 s[66:67], s[14:15], exec
	s_cselect_b32 s54, s69, s29
	s_cselect_b32 s63, s68, s28
	s_ashr_i32 s61, s60, 31
	s_lshl_b64 s[66:67], s[60:61], 19
	v_readlane_b32 s70, v254, 5
	v_readlane_b32 s71, v254, 6
	s_add_u32 s66, s70, s66
	s_addc_u32 s67, s71, s67
	s_and_b64 s[70:71], s[14:15], exec
	s_cselect_b32 s61, s67, s27
	s_cselect_b32 s88, s66, s26
	v_lshl_add_u64 v[134:135], s[28:29], 0, v[142:143]
	s_mov_b32 s89, -2
	s_mov_b64 s[26:27], 0
	v_add_u32_e32 v236, s72, v163
	v_add_u32_e32 v237, s72, v164
	v_add_u32_e32 v238, s73, v163
	v_add_u32_e32 v239, s73, v164
	v_add_u32_e32 v240, s77, v163
	v_add_u32_e32 v241, s77, v164
	v_add_u32_e32 v242, s79, v163
	v_add_u32_e32 v243, s79, v164
	v_add_u32_e32 v244, s82, v163
	v_add_u32_e32 v245, s82, v164
	v_add_u32_e32 v246, s80, v163
	v_add_u32_e32 v247, s80, v164
	v_add_u32_e32 v248, s83, v163
	v_add_u32_e32 v249, s83, v164
	v_add_u32_e32 v250, s81, v163
	v_add_u32_e32 v251, s81, v164
.LBB0_973:
	ds_read_b128 v[136:139], v236
	ds_read_b128 v[148:151], v237
	s_add_u32 s70, s28, s26
	s_waitcnt lgkmcnt(0)
	ds_read_b128 v[152:155], v238
	ds_read_b128 v[174:177], v239
	s_addc_u32 s71, s29, s27
	ds_read_b128 v[178:181], v240
	ds_read_b128 v[182:185], v241
	s_add_u32 s70, s70, 0x100
	ds_read_b128 v[196:199], v242
	ds_read_b128 v[200:203], v243
	s_addc_u32 s71, s71, 0
	s_add_u32 s86, s65, s26
	s_addc_u32 s87, s85, s27
	s_cmpk_eq_i32 s26, 0x700
	s_cselect_b32 s87, s61, s87
	s_cselect_b32 s86, s88, s86
	s_cselect_b32 s71, s54, s71
	s_cselect_b32 s70, s63, s70
	v_lshl_add_u64 v[140:141], v[134:135], 0, s[26:27]
	v_lshl_add_u64 v[160:161], v[140:141], 0, s[36:37]
	s_add_i32 m0, s5, 0x8000
	s_mov_b64 s[90:91], 0x20080
	ds_read_b128 v[204:207], v166
	ds_read_b128 v[208:211], v166 offset:2048
	ds_read_b128 v[212:215], v167
	ds_read_b128 v[216:219], v167 offset:2048
	ds_read_b128 v[220:223], v166 offset:4096
	ds_read_b128 v[224:227], v166 offset:6144
	ds_read_b128 v[228:231], v167 offset:4096
	ds_read_b128 v[232:235], v167 offset:6144
	global_load_lds_dwordx4 v[160:161], off
	v_lshl_add_u64 v[160:161], v[140:141], 0, s[90:91]
	s_add_i32 m0, s5, 0xa000
	s_mov_b64 s[90:91], 0x60080
	global_load_lds_dwordx4 v[160:161], off
	v_lshl_add_u64 v[160:161], v[140:141], 0, s[44:45]
	s_add_i32 m0, s5, 0xc000
	v_lshl_add_u64 v[140:141], v[140:141], 0, s[90:91]
	global_load_lds_dwordx4 v[160:161], off
	s_add_i32 m0, s5, 0xe000
	s_nop 0
	global_load_lds_dwordx4 v[140:141], off
	s_waitcnt vmcnt(8)
	s_waitcnt lgkmcnt(0)
	s_barrier
	v_mfma_f32_16x16x32_bf16 v[8:11], v[136:139], v[204:207], v[8:11]
	v_mfma_f32_16x16x32_bf16 v[8:11], v[148:151], v[212:215], v[8:11]
	v_mfma_f32_16x16x32_bf16 v[12:15], v[148:151], v[216:219], v[12:15]
	v_mfma_f32_16x16x32_bf16 v[12:15], v[136:139], v[208:211], v[12:15]
	v_mfma_f32_16x16x32_bf16 v[44:47], v[136:139], v[220:223], v[44:47]
	v_mfma_f32_16x16x32_bf16 v[44:47], v[148:151], v[228:231], v[44:47]
	v_mfma_f32_16x16x32_bf16 v[20:23], v[148:151], v[232:235], v[20:23]
	v_mfma_f32_16x16x32_bf16 v[20:23], v[136:139], v[224:227], v[20:23]
	v_mfma_f32_16x16x32_bf16 v[24:27], v[152:155], v[224:227], v[24:27]
	v_mfma_f32_16x16x32_bf16 v[24:27], v[174:177], v[232:235], v[24:27]
	v_mfma_f32_16x16x32_bf16 v[36:39], v[174:177], v[228:231], v[36:39]
	v_mfma_f32_16x16x32_bf16 v[36:39], v[152:155], v[220:223], v[36:39]
	v_mfma_f32_16x16x32_bf16 v[16:19], v[152:155], v[208:211], v[16:19]
	v_mfma_f32_16x16x32_bf16 v[16:19], v[174:177], v[216:219], v[16:19]
	v_mfma_f32_16x16x32_bf16 v[4:7], v[174:177], v[212:215], v[4:7]
	v_mfma_f32_16x16x32_bf16 v[4:7], v[152:155], v[204:207], v[4:7]
	v_mfma_f32_16x16x32_bf16 v[32:35], v[178:181], v[204:207], v[32:35]
	v_mfma_f32_16x16x32_bf16 v[32:35], v[182:185], v[212:215], v[32:35]
	v_mfma_f32_16x16x32_bf16 v[40:43], v[182:185], v[216:219], v[40:43]
	v_mfma_f32_16x16x32_bf16 v[40:43], v[178:181], v[208:211], v[40:43]
	v_mfma_f32_16x16x32_bf16 v[48:51], v[178:181], v[220:223], v[48:51]
	v_mfma_f32_16x16x32_bf16 v[48:51], v[182:185], v[228:231], v[48:51]
	v_mfma_f32_16x16x32_bf16 v[56:59], v[182:185], v[232:235], v[56:59]
	v_mfma_f32_16x16x32_bf16 v[56:59], v[178:181], v[224:227], v[56:59]
	v_mfma_f32_16x16x32_bf16 v[64:67], v[196:199], v[224:227], v[64:67]
	v_mfma_f32_16x16x32_bf16 v[64:67], v[200:203], v[232:235], v[64:67]
	v_mfma_f32_16x16x32_bf16 v[60:63], v[200:203], v[228:231], v[60:63]
	v_mfma_f32_16x16x32_bf16 v[60:63], v[196:199], v[220:223], v[60:63]
	v_mfma_f32_16x16x32_bf16 v[52:55], v[196:199], v[208:211], v[52:55]
	v_mfma_f32_16x16x32_bf16 v[52:55], v[200:203], v[216:219], v[52:55]
	v_mfma_f32_16x16x32_bf16 v[28:31], v[200:203], v[212:215], v[28:31]
	v_mfma_f32_16x16x32_bf16 v[28:31], v[196:199], v[204:207], v[28:31]
	s_barrier
	v_lshl_add_u64 v[140:141], s[86:87], 0, v[158:159]
	s_add_i32 s86, s72, s34
	s_mov_b32 m0, s86
	ds_read_b128 v[204:207], v166 offset:16384
	ds_read_b128 v[208:211], v166 offset:18432
	ds_read_b128 v[212:215], v167 offset:16384
	ds_read_b128 v[216:219], v167 offset:18432
	ds_read_b128 v[220:223], v166 offset:20480
	ds_read_b128 v[224:227], v166 offset:22528
	ds_read_b128 v[228:231], v167 offset:20480
	ds_read_b128 v[232:235], v167 offset:22528
	global_load_lds_dwordx4 v[140:141], off
	v_lshl_add_u64 v[160:161], v[140:141], 0, s[18:19]
	s_add_i32 m0, s86, 0x2000
	s_mov_b64 s[86:87], 0x10000
	global_load_lds_dwordx4 v[160:161], off
	v_lshl_add_u64 v[160:161], v[140:141], 0, s[86:87]
	s_add_i32 s86, s77, s34
	s_mov_b32 m0, s86
	s_nop 0
	global_load_lds_dwordx4 v[160:161], off
	v_lshl_add_u64 v[160:161], v[140:141], 0, s[20:21]
	s_add_i32 m0, s86, 0x2000
	s_nop 0
	global_load_lds_dwordx4 v[160:161], off
	s_waitcnt vmcnt(4)
	s_waitcnt lgkmcnt(0)
	s_barrier
	v_mfma_f32_16x16x32_bf16 v[68:71], v[136:139], v[204:207], v[68:71]
	v_mfma_f32_16x16x32_bf16 v[68:71], v[148:151], v[212:215], v[68:71]
	v_mfma_f32_16x16x32_bf16 v[92:95], v[148:151], v[216:219], v[92:95]
	v_mfma_f32_16x16x32_bf16 v[92:95], v[136:139], v[208:211], v[92:95]
	v_mfma_f32_16x16x32_bf16 v[76:79], v[136:139], v[220:223], v[76:79]
	v_mfma_f32_16x16x32_bf16 v[76:79], v[148:151], v[228:231], v[76:79]
	v_mfma_f32_16x16x32_bf16 v[116:119], v[148:151], v[232:235], v[116:119]
	v_mfma_f32_16x16x32_bf16 v[116:119], v[136:139], v[224:227], v[116:119]
	v_mfma_f32_16x16x32_bf16 v[108:111], v[152:155], v[224:227], v[108:111]
	v_mfma_f32_16x16x32_bf16 v[108:111], v[174:177], v[232:235], v[108:111]
	v_mfma_f32_16x16x32_bf16 v[80:83], v[174:177], v[228:231], v[80:83]
	v_mfma_f32_16x16x32_bf16 v[80:83], v[152:155], v[220:223], v[80:83]
	v_mfma_f32_16x16x32_bf16 v[84:87], v[152:155], v[208:211], v[84:87]
	v_mfma_f32_16x16x32_bf16 v[84:87], v[174:177], v[216:219], v[84:87]
	v_mfma_f32_16x16x32_bf16 v[72:75], v[174:177], v[212:215], v[72:75]
	v_mfma_f32_16x16x32_bf16 v[72:75], v[152:155], v[204:207], v[72:75]
	v_mfma_f32_16x16x32_bf16 v[88:91], v[178:181], v[204:207], v[88:91]
	v_mfma_f32_16x16x32_bf16 v[88:91], v[182:185], v[212:215], v[88:91]
	v_mfma_f32_16x16x32_bf16 v[96:99], v[182:185], v[216:219], v[96:99]
	v_mfma_f32_16x16x32_bf16 v[96:99], v[178:181], v[208:211], v[96:99]
	v_mfma_f32_16x16x32_bf16 v[112:115], v[178:181], v[220:223], v[112:115]
	v_mfma_f32_16x16x32_bf16 v[112:115], v[182:185], v[228:231], v[112:115]
	v_mfma_f32_16x16x32_bf16 v[120:123], v[182:185], v[232:235], v[120:123]
	v_mfma_f32_16x16x32_bf16 v[120:123], v[178:181], v[224:227], v[120:123]
	v_mfma_f32_16x16x32_bf16 v[128:131], v[196:199], v[224:227], v[128:131]
	v_mfma_f32_16x16x32_bf16 v[128:131], v[200:203], v[232:235], v[128:131]
	v_mfma_f32_16x16x32_bf16 v[124:127], v[200:203], v[228:231], v[124:127]
	v_mfma_f32_16x16x32_bf16 v[124:127], v[196:199], v[220:223], v[124:127]
	v_mfma_f32_16x16x32_bf16 v[104:107], v[196:199], v[208:211], v[104:107]
	v_mfma_f32_16x16x32_bf16 v[104:107], v[200:203], v[216:219], v[104:107]
	v_mfma_f32_16x16x32_bf16 v[100:103], v[200:203], v[212:215], v[100:103]
	v_mfma_f32_16x16x32_bf16 v[100:103], v[196:199], v[204:207], v[100:103]
	s_barrier
	ds_read_b128 v[136:139], v244
	ds_read_b128 v[148:151], v245
	ds_read_b128 v[152:155], v246
	ds_read_b128 v[174:177], v247
	ds_read_b128 v[178:181], v248
	ds_read_b128 v[182:185], v249
	ds_read_b128 v[196:199], v250
	ds_read_b128 v[200:203], v251
	s_mov_b32 m0, s5
	v_lshl_add_u64 v[160:161], s[70:71], 0, v[0:1]
	s_mov_b64 s[70:71], 0x20000
	ds_read_b128 v[204:207], v166 offset:32768
	ds_read_b128 v[208:211], v166 offset:34816
	ds_read_b128 v[212:215], v167 offset:32768
	ds_read_b128 v[216:219], v167 offset:34816
	ds_read_b128 v[220:223], v166 offset:36864
	ds_read_b128 v[224:227], v166 offset:38912
	ds_read_b128 v[228:231], v167 offset:36864
	ds_read_b128 v[232:235], v167 offset:38912
	global_load_lds_dwordx4 v[160:161], off
	v_lshl_add_u64 v[170:171], v[160:161], 0, s[70:71]
	s_mov_b32 m0, s17
	s_nop 0
	global_load_lds_dwordx4 v[170:171], off
	v_lshl_add_u64 v[170:171], v[160:161], 0, s[18:19]
	s_mov_b32 m0, s35
	v_lshl_add_u64 v[160:161], v[160:161], 0, s[22:23]
	global_load_lds_dwordx4 v[170:171], off
	s_mov_b32 m0, s38
	s_nop 0
	global_load_lds_dwordx4 v[160:161], off
	s_waitcnt vmcnt(8)
	s_waitcnt lgkmcnt(0)
	s_barrier
	v_mfma_f32_16x16x32_bf16 v[8:11], v[136:139], v[204:207], v[8:11]
	v_mfma_f32_16x16x32_bf16 v[8:11], v[148:151], v[212:215], v[8:11]
	v_mfma_f32_16x16x32_bf16 v[12:15], v[148:151], v[216:219], v[12:15]
	v_mfma_f32_16x16x32_bf16 v[12:15], v[136:139], v[208:211], v[12:15]
	v_mfma_f32_16x16x32_bf16 v[44:47], v[136:139], v[220:223], v[44:47]
	v_mfma_f32_16x16x32_bf16 v[44:47], v[148:151], v[228:231], v[44:47]
	v_mfma_f32_16x16x32_bf16 v[20:23], v[148:151], v[232:235], v[20:23]
	v_mfma_f32_16x16x32_bf16 v[20:23], v[136:139], v[224:227], v[20:23]
	v_mfma_f32_16x16x32_bf16 v[24:27], v[152:155], v[224:227], v[24:27]
	v_mfma_f32_16x16x32_bf16 v[24:27], v[174:177], v[232:235], v[24:27]
	v_mfma_f32_16x16x32_bf16 v[36:39], v[174:177], v[228:231], v[36:39]
	v_mfma_f32_16x16x32_bf16 v[36:39], v[152:155], v[220:223], v[36:39]
	v_mfma_f32_16x16x32_bf16 v[16:19], v[152:155], v[208:211], v[16:19]
	v_mfma_f32_16x16x32_bf16 v[16:19], v[174:177], v[216:219], v[16:19]
	v_mfma_f32_16x16x32_bf16 v[4:7], v[174:177], v[212:215], v[4:7]
	v_mfma_f32_16x16x32_bf16 v[4:7], v[152:155], v[204:207], v[4:7]
	v_mfma_f32_16x16x32_bf16 v[32:35], v[178:181], v[204:207], v[32:35]
	v_mfma_f32_16x16x32_bf16 v[32:35], v[182:185], v[212:215], v[32:35]
	v_mfma_f32_16x16x32_bf16 v[40:43], v[182:185], v[216:219], v[40:43]
	v_mfma_f32_16x16x32_bf16 v[40:43], v[178:181], v[208:211], v[40:43]
	v_mfma_f32_16x16x32_bf16 v[48:51], v[178:181], v[220:223], v[48:51]
	v_mfma_f32_16x16x32_bf16 v[48:51], v[182:185], v[228:231], v[48:51]
	v_mfma_f32_16x16x32_bf16 v[56:59], v[182:185], v[232:235], v[56:59]
	v_mfma_f32_16x16x32_bf16 v[56:59], v[178:181], v[224:227], v[56:59]
	v_mfma_f32_16x16x32_bf16 v[64:67], v[196:199], v[224:227], v[64:67]
	v_mfma_f32_16x16x32_bf16 v[64:67], v[200:203], v[232:235], v[64:67]
	v_mfma_f32_16x16x32_bf16 v[60:63], v[200:203], v[228:231], v[60:63]
	v_mfma_f32_16x16x32_bf16 v[60:63], v[196:199], v[220:223], v[60:63]
	v_mfma_f32_16x16x32_bf16 v[52:55], v[196:199], v[208:211], v[52:55]
	v_mfma_f32_16x16x32_bf16 v[52:55], v[200:203], v[216:219], v[52:55]
	v_mfma_f32_16x16x32_bf16 v[28:31], v[200:203], v[212:215], v[28:31]
	v_mfma_f32_16x16x32_bf16 v[28:31], v[196:199], v[204:207], v[28:31]
	s_barrier
	s_add_i32 s70, s82, s34
	v_lshl_add_u64 v[160:161], v[140:141], 0, s[36:37]
	s_mov_b32 m0, s70
	ds_read_b128 v[204:207], v166 offset:49152
	ds_read_b128 v[208:211], v166 offset:51200
	ds_read_b128 v[212:215], v167 offset:49152
	ds_read_b128 v[216:219], v167 offset:51200
	ds_read_b128 v[220:223], v166 offset:53248
	ds_read_b128 v[224:227], v166 offset:55296
	ds_read_b128 v[228:231], v167 offset:53248
	ds_read_b128 v[232:235], v167 offset:55296
	global_load_lds_dwordx4 v[160:161], off
	v_lshl_add_u64 v[160:161], v[140:141], 0, s[44:45]
	s_add_i32 m0, s70, 0x2000
	s_add_i32 s70, s83, s34
	global_load_lds_dwordx4 v[160:161], off
	v_lshl_add_u64 v[160:161], v[140:141], 0, s[46:47]
	s_mov_b32 m0, s70
	v_lshl_add_u64 v[140:141], v[140:141], 0, s[50:51]
	global_load_lds_dwordx4 v[160:161], off
	s_add_i32 m0, s70, 0x2000
	s_nop 0
	global_load_lds_dwordx4 v[140:141], off
	s_waitcnt vmcnt(4)
	s_waitcnt lgkmcnt(0)
	s_barrier
	v_mfma_f32_16x16x32_bf16 v[68:71], v[136:139], v[204:207], v[68:71]
	v_mfma_f32_16x16x32_bf16 v[68:71], v[148:151], v[212:215], v[68:71]
	v_mfma_f32_16x16x32_bf16 v[92:95], v[148:151], v[216:219], v[92:95]
	v_mfma_f32_16x16x32_bf16 v[92:95], v[136:139], v[208:211], v[92:95]
	v_mfma_f32_16x16x32_bf16 v[76:79], v[136:139], v[220:223], v[76:79]
	v_mfma_f32_16x16x32_bf16 v[76:79], v[148:151], v[228:231], v[76:79]
	v_mfma_f32_16x16x32_bf16 v[116:119], v[148:151], v[232:235], v[116:119]
	v_mfma_f32_16x16x32_bf16 v[116:119], v[136:139], v[224:227], v[116:119]
	v_mfma_f32_16x16x32_bf16 v[108:111], v[152:155], v[224:227], v[108:111]
	v_mfma_f32_16x16x32_bf16 v[108:111], v[174:177], v[232:235], v[108:111]
	v_mfma_f32_16x16x32_bf16 v[80:83], v[174:177], v[228:231], v[80:83]
	v_mfma_f32_16x16x32_bf16 v[80:83], v[152:155], v[220:223], v[80:83]
	v_mfma_f32_16x16x32_bf16 v[84:87], v[152:155], v[208:211], v[84:87]
	v_mfma_f32_16x16x32_bf16 v[84:87], v[174:177], v[216:219], v[84:87]
	v_mfma_f32_16x16x32_bf16 v[72:75], v[174:177], v[212:215], v[72:75]
	v_mfma_f32_16x16x32_bf16 v[72:75], v[152:155], v[204:207], v[72:75]
	v_mfma_f32_16x16x32_bf16 v[88:91], v[178:181], v[204:207], v[88:91]
	v_mfma_f32_16x16x32_bf16 v[88:91], v[182:185], v[212:215], v[88:91]
	v_mfma_f32_16x16x32_bf16 v[96:99], v[182:185], v[216:219], v[96:99]
	v_mfma_f32_16x16x32_bf16 v[96:99], v[178:181], v[208:211], v[96:99]
	v_mfma_f32_16x16x32_bf16 v[112:115], v[178:181], v[220:223], v[112:115]
	v_mfma_f32_16x16x32_bf16 v[112:115], v[182:185], v[228:231], v[112:115]
	v_mfma_f32_16x16x32_bf16 v[120:123], v[182:185], v[232:235], v[120:123]
	v_mfma_f32_16x16x32_bf16 v[120:123], v[178:181], v[224:227], v[120:123]
	v_mfma_f32_16x16x32_bf16 v[128:131], v[196:199], v[224:227], v[128:131]
	v_mfma_f32_16x16x32_bf16 v[128:131], v[200:203], v[232:235], v[128:131]
	v_mfma_f32_16x16x32_bf16 v[124:127], v[200:203], v[228:231], v[124:127]
	v_mfma_f32_16x16x32_bf16 v[124:127], v[196:199], v[220:223], v[124:127]
	v_mfma_f32_16x16x32_bf16 v[104:107], v[196:199], v[208:211], v[104:107]
	v_mfma_f32_16x16x32_bf16 v[104:107], v[200:203], v[216:219], v[104:107]
	v_mfma_f32_16x16x32_bf16 v[100:103], v[200:203], v[212:215], v[100:103]
	v_mfma_f32_16x16x32_bf16 v[100:103], v[196:199], v[204:207], v[100:103]
	s_barrier
	s_add_i32 s89, s89, 2
	s_add_u32 s26, s26, 0x100
	s_addc_u32 s27, s27, 0
	s_cmp_gt_u32 s89, 13
	s_cbranch_scc0 .LBB0_973
	s_and_b64 vcc, exec, s[52:53]
	s_cbranch_vccz .LBB0_976
	s_barrier
